# layer 0 attention idle tail now runs the last 288 prep items (two for half of the idle workgroups); prep ticket loop stops at item 864
# speedup vs baseline: 1.0294x; 1.0037x over previous
prep_items_l0:
	s_add_u32 s6, s34, 0x1c4000
	s_addc_u32 s7, s35, 0
	s_add_u32 s8, s34, 0x1c2000
	s_addc_u32 s9, s35, 0
	s_add_u32 s10, s34, 0x1c6000
	s_addc_u32 s11, s35, 0
	s_add_u32 s70, s34, 0xda000
	s_addc_u32 s71, s35, 0
	s_add_i32 s4, 0, 0x20180
	s_mov_b32 s73, 0
	v_mov_b32_e32 v123, 0
	v_mov_b32_e32 v1, s4
	s_movk_i32 s5, 0x47f
	s_movk_i32 s19, 0x90
	s_movk_i32 s22, 0x3800
	s_movk_i32 s23, 0xc00
	s_movk_i32 s27, 0x800
	s_mov_b32 s33, 0xffff0000
	s_movk_i32 s44, 0x7fff
	v_mov_b32_e32 v127, 0x358637bd
	s_mov_b32 s45, 0xf800000
	v_mov_b32_e32 v129, 0x260
	s_movk_i32 s48, 0x110
	s_cmpk_lg_i32 s94, 0x100
	s_cbranch_scc1 it_mode_done_l0
	s_cmp_lg_u32 s100, 0
	s_cbranch_scc1 it_mode_done_l0
	s_movk_i32 s5, 0x35f

it_tail_tk_l0:
	v_mov_b32_e32 v3, s101
	s_mov_b32 s101, s99
	s_movk_i32 s99, 0x7fff

.LBB0_568:
	s_cmpk_lg_i32 s94, 0x100
	s_cbranch_scc1 attn_tail_done_l0
	s_and_b32 s101, s2, 7
	s_cmpk_lt_u32 s101, 2
	s_cbranch_scc1 attn_tail_done_l0
	s_add_i32 s101, s101, -2
	s_lshl_b32 s101, s101, 5
	s_lshr_b32 s100, s2, 3
	s_add_i32 s101, s101, s100
	s_movk_i32 s99, 0x7fff
	s_cmpk_ge_u32 s100, 16
	s_cbranch_scc1 attn_tail_one_l0
	s_lshr_b32 s99, s101, 5
	s_lshl_b32 s99, s99, 4
	s_add_i32 s99, s99, s100
	s_addk_i32 s99, 0x420
attn_tail_one_l0:
	s_addk_i32 s101, 0x360
	s_mov_b32 s100, 1
	s_add_u32 s14, s34, 0x5900000
	s_addc_u32 s15, s35, 0
	s_add_u32 s52, s34, 0x8f00000
	s_addc_u32 s53, s35, 0
	s_add_u32 s68, s34, 0x1c0000
	s_addc_u32 s69, s35, 0
	s_branch prep_items_l0
